# attention: the lse(prev) load is now waited at its consumer (vmcnt(16)) instead of by vmcnt(12) right after the prefetch issue, so compute no longer waits on the previous unit's store acks
# speedup vs baseline: 1.0039x; 1.0039x over previous
; __device__ __forceinline__ void attn_phase(LAS unsigned char* lds, const bf16_t* qp, const bf16_t* kvp, bf16_t* obuf, float* lse, const float* biasG, const int gi, const int rsh, const int G) {
;     ...
;         ATT_EXP8(0, 0); ATT_EXP8(0, 8);
;         bf16_t* og = obuf + ((size_t)h * M + growq) * 64 + 8 * hi;
;         u32x4 prev[2][2];
;         f32x16 o[2];
; #pragma unroll
;         for (int r = 0; r < 16; ++r) { o[0][r] = 0.f; o[1][r] = 0.f; }
;         const LAS unsigned char* vb = lds + A_V0 + ((lane >> 4) & 1) * 32 + (lane & 3) * 8 + (4 * hi + ((lane & 15) >> 2)) * 64;
; #pragma unroll
;         for (int cc = 0; cc < 5; ++cc)
; #pragma unroll
;             for (int gk = 0; gk < 2; ++gk) {
;                 if (cc == 3 && gk == 0 && gi > 0) {
; #pragma unroll
;                     for (int d0 = 0; d0 < 2; ++d0)
; #pragma unroll
;                         for (int pr = 0; pr < 2; ++pr) prev[d0][pr] = gld<u32x4>(og + 32 * d0 + 16 * pr);
;                 }
;                 if (cc + 1 < 5) ATT_EXP8(cc + 1 < 5 ? cc + 1 : cc, 8 * gk);
;                 u32x4 pw; pw.x = cvt_pk_bf16(p[cc][8 * gk + 0], p[cc][8 * gk + 1]); pw.y = cvt_pk_bf16(p[cc][8 * gk + 2], p[cc][8 * gk + 3]);
;                 pw.z = cvt_pk_bf16(p[cc][8 * gk + 4], p[cc][8 * gk + 5]); pw.w = cvt_pk_bf16(p[cc][8 * gk + 6], p[cc][8 * gk + 7]);
;                 const bf16x8 pa = __builtin_bit_cast(bf16x8, pw);
;                 const LAS unsigned char* vrow = vb + sc[cc] * 2048 + gk * 1024;
; #pragma unroll
;                 for (int d0 = 0; d0 < 2; ++d0) {
;                     const v4i16_t lo = vtr(vrow + d0 * VHS), hh = vtr(vrow + d0 * VHS + 512);
;                     const bf16x8 vf = (bf16x8){lo[0], lo[1], lo[2], lo[3], hh[0], hh[1], hh[2], hh[3]};
;                     o[d0] = __builtin_amdgcn_mfma_f32_32x32x16_bf16(vf, pa, o[d0], 0, 0, 0);
;                 }
;             }
;     ...
;         float l = l2.x + l2.y;
;         l += __shfl_xor(l, 32);
;         const float lse_new = mx + __builtin_amdgcn_logf(l);
;         float ca = 0.f, cb = 1.0f / l, lse_out = lse_new;
;         if (gi > 0) {
;             const float mm = fmaxf(lp, lse_new);
;             const float wa = __builtin_amdgcn_exp2f(lp - mm), wb = __builtin_amdgcn_exp2f(lse_new - mm), tot = wa + wb, it = 1.0f / tot;
;             ca = wa * it; cb = wb * it / l; lse_out = mm + __builtin_amdgcn_logf(tot);
.LBB0_117:
	v_pk_add_f32 v[74:75], v[202:203], 0 op_sel_hi:[1,0]
	v_mov_b32_e32 v201, v200
	v_pk_add_f32 v[74:75], v[204:205], v[74:75]
	v_pk_add_f32 v[48:49], v[48:49], v[200:201] neg_lo:[0,1] neg_hi:[0,1]
	v_pk_add_f32 v[74:75], v[206:207], v[74:75]
	v_exp_f32_e32 v48, v48
	v_pk_add_f32 v[74:75], v[208:209], v[74:75]
	v_exp_f32_e32 v49, v49
	v_pk_add_f32 v[74:75], v[210:211], v[74:75]
	v_pk_add_f32 v[50:51], v[50:51], v[200:201] neg_lo:[0,1] neg_hi:[0,1]
	v_pk_add_f32 v[74:75], v[212:213], v[74:75]
	v_exp_f32_e32 v50, v50
	v_pk_add_f32 v[74:75], v[214:215], v[74:75]
	v_exp_f32_e32 v51, v51
	v_pk_add_f32 v[74:75], v[216:217], v[74:75]
	v_pk_add_f32 v[52:53], v[52:53], v[200:201] neg_lo:[0,1] neg_hi:[0,1]
	v_pk_add_f32 v[74:75], v[80:81], v[74:75]
	v_exp_f32_e32 v52, v52
	v_pk_add_f32 v[74:75], v[218:219], v[74:75]
	v_exp_f32_e32 v53, v53
	v_pk_add_f32 v[74:75], v[84:85], v[74:75]
	v_pk_add_f32 v[54:55], v[54:55], v[200:201] neg_lo:[0,1] neg_hi:[0,1]
	v_pk_add_f32 v[74:75], v[82:83], v[74:75]
	v_exp_f32_e32 v54, v54
	v_pk_add_f32 v[74:75], v[220:221], v[74:75]
	v_exp_f32_e32 v55, v55
	v_pk_add_f32 v[74:75], v[90:91], v[74:75]
	v_pk_add_f32 v[56:57], v[56:57], v[200:201] neg_lo:[0,1] neg_hi:[0,1]
	v_pk_add_f32 v[74:75], v[88:89], v[74:75]
	v_exp_f32_e32 v56, v56
	v_pk_add_f32 v[74:75], v[86:87], v[74:75]
	v_exp_f32_e32 v57, v57
	v_pk_add_f32 v[74:75], v[94:95], v[74:75]
	v_pk_add_f32 v[58:59], v[58:59], v[200:201] neg_lo:[0,1] neg_hi:[0,1]
	v_pk_add_f32 v[74:75], v[92:93], v[74:75]
	v_pk_add_f32 v[32:33], v[32:33], v[200:201] neg_lo:[0,1] neg_hi:[0,1]
	v_pk_add_f32 v[66:67], v[66:67], v[74:75]
	v_exp_f32_e32 v58, v58
	v_pk_add_f32 v[64:65], v[64:65], v[66:67]
	v_exp_f32_e32 v59, v59
	v_pk_add_f32 v[64:65], v[222:223], v[64:65]
	v_pk_add_f32 v[60:61], v[60:61], v[200:201] neg_lo:[0,1] neg_hi:[0,1]
	v_pk_add_f32 v[64:65], v[72:73], v[64:65]
	v_lshl_add_u32 v72, s22, 11, v244
	v_pk_add_f32 v[64:65], v[70:71], v[64:65]
	v_exp_f32_e32 v66, v32
	v_pk_add_f32 v[64:65], v[68:69], v[64:65]
	v_exp_f32_e32 v67, v33
	v_pk_add_f32 v[64:65], v[48:49], v[64:65]
	v_pk_add_f32 v[32:33], v[34:35], v[200:201] neg_lo:[0,1] neg_hi:[0,1]
	v_pk_add_f32 v[64:65], v[50:51], v[64:65]
	v_add_u32_e32 v73, 0xc080, v72
	v_pk_add_f32 v[64:65], v[52:53], v[64:65]
	v_exp_f32_e32 v60, v60
	v_pk_add_f32 v[64:65], v[54:55], v[64:65]
	v_exp_f32_e32 v61, v61
	v_pk_add_f32 v[62:63], v[62:63], v[200:201] neg_lo:[0,1] neg_hi:[0,1]
	v_cvt_pk_bf16_f32 v48, v48, v49
	v_cvt_pk_bf16_f32 v49, v50, v51
	v_cvt_pk_bf16_f32 v50, v52, v53
	v_cvt_pk_bf16_f32 v51, v54, v55
	ds_read_b64_tr_b16 v[52:53], v72 offset:49280
	ds_read_b64_tr_b16 v[54:55], v72 offset:49792
	v_exp_f32_e32 v68, v32
	v_exp_f32_e32 v69, v33
	ds_read_b64_tr_b16 v[32:33], v73 offset:24640
	ds_read_b64_tr_b16 v[34:35], v73 offset:25152
	v_exp_f32_e32 v62, v62
	v_exp_f32_e32 v63, v63
	v_pk_add_f32 v[64:65], v[56:57], v[64:65]
	v_pk_add_f32 v[36:37], v[36:37], v[200:201] neg_lo:[0,1] neg_hi:[0,1]
	v_pk_add_f32 v[64:65], v[58:59], v[64:65]
	v_exp_f32_e32 v70, v36
	v_pk_add_f32 v[64:65], v[60:61], v[64:65]
	v_exp_f32_e32 v71, v37
	v_pk_add_f32 v[64:65], v[62:63], v[64:65]
	v_pk_add_f32 v[36:37], v[38:39], v[200:201] neg_lo:[0,1] neg_hi:[0,1]
	s_waitcnt lgkmcnt(0)
	v_mfma_f32_32x32x16_bf16 v[0:15], v[32:35], v[48:51], v[0:15]
	v_add_f32_e64 v40, v40, -v200
	v_add_f32_e64 v41, v41, -v201
	v_cvt_pk_bf16_f32 v32, v56, v57
	v_cvt_pk_bf16_f32 v33, v58, v59
	v_cvt_pk_bf16_f32 v34, v60, v61
	v_cvt_pk_bf16_f32 v35, v62, v63
	v_add_f32_e64 v44, v44, -v200
	v_add_f32_e64 v45, v45, -v201
	v_exp_f32_e32 v56, v40
	v_mfma_f32_32x32x16_bf16 v[16:31], v[52:55], v[48:51], v[16:31]
	v_exp_f32_e32 v52, v36
	v_exp_f32_e32 v53, v37
	v_pk_add_f32 v[36:37], v[66:67], v[64:65]
	v_exp_f32_e32 v57, v41
	v_pk_add_f32 v[36:37], v[68:69], v[36:37]
	v_pk_add_f32 v[40:41], v[42:43], v[200:201] neg_lo:[0,1] neg_hi:[0,1]
	v_pk_add_f32 v[54:55], v[70:71], v[36:37]
	ds_read_b64_tr_b16 v[36:37], v72 offset:50304
	ds_read_b64_tr_b16 v[38:39], v72 offset:50816
	v_exp_f32_e32 v58, v40
	v_exp_f32_e32 v59, v41
	ds_read_b64_tr_b16 v[40:41], v73 offset:25664
	ds_read_b64_tr_b16 v[42:43], v73 offset:26176
	s_waitcnt lgkmcnt(0)
	v_mfma_f32_32x32x16_bf16 v[0:15], v[40:43], v[32:35], v[0:15]
	v_lshl_add_u32 v64, s4, 11, v244
	v_add_u32_e32 v65, 0xc080, v64
	v_exp_f32_e32 v60, v44
	v_exp_f32_e32 v61, v45
	v_pk_add_f32 v[40:41], v[46:47], v[200:201] neg_lo:[0,1] neg_hi:[0,1]
	s_and_b64 vcc, exec, s[54:55]
	v_exp_f32_e32 v62, v40
	v_mfma_f32_32x32x16_bf16 v[16:31], v[36:39], v[32:35], v[16:31]
	v_cvt_pk_bf16_f32 v36, v66, v67
	v_cvt_pk_bf16_f32 v37, v68, v69
	v_cvt_pk_bf16_f32 v38, v70, v71
	v_cvt_pk_bf16_f32 v39, v52, v53
	ds_read_b64_tr_b16 v[48:49], v64 offset:49280
	ds_read_b64_tr_b16 v[50:51], v64 offset:49792
	ds_read_b64_tr_b16 v[32:33], v65 offset:24640
	ds_read_b64_tr_b16 v[34:35], v65 offset:25152
	v_exp_f32_e32 v63, v41
	s_waitcnt lgkmcnt(0)
	v_mfma_f32_32x32x16_bf16 v[0:15], v[32:35], v[36:39], v[0:15]
	v_add_f32_e64 v32, v52, v54
	v_add_f32_e64 v33, v53, v55
	v_cvt_pk_bf16_f32 v40, v56, v57
	v_cvt_pk_bf16_f32 v41, v58, v59
	v_cvt_pk_bf16_f32 v42, v60, v61
	v_cvt_pk_bf16_f32 v43, v62, v63
	ds_read_b64_tr_b16 v[44:45], v64 offset:50304
	ds_read_b64_tr_b16 v[46:47], v64 offset:50816
	v_add_f32_e64 v32, v56, v32
	v_add_f32_e64 v33, v57, v33
	v_mfma_f32_32x32x16_bf16 v[16:31], v[48:51], v[36:39], v[16:31]
	v_add_f32_e64 v32, v58, v32
	v_add_f32_e64 v33, v59, v33
	ds_read_b64_tr_b16 v[36:37], v65 offset:25664
	ds_read_b64_tr_b16 v[38:39], v65 offset:26176
	v_add_f32_e64 v32, v60, v32
	v_add_f32_e64 v33, v61, v33
	v_pk_add_f32 v[32:33], v[62:63], v[32:33]
	s_nop 0
	v_add_f32_e32 v32, v32, v33
	ds_bpermute_b32 v33, v228, v32
	s_waitcnt lgkmcnt(3)
	v_mfma_f32_32x32x16_bf16 v[16:31], v[44:47], v[40:43], v[16:31]
	s_waitcnt lgkmcnt(0)
	v_add_f32_e32 v34, v32, v33
	v_log_f32_e32 v32, v34
	s_nop 0
	v_add_f32_e32 v35, v200, v32
	v_mfma_f32_32x32x16_bf16 v[0:15], v[36:39], v[40:43], v[0:15]
	s_cbranch_vccnz .LBB0_119
	v_max_f32_e32 v32, v35, v35
	s_waitcnt vmcnt(16)
	v_max_f32_e32 v33, v252, v252
	v_max_f32_e32 v37, v33, v32
	v_sub_f32_e32 v32, v252, v37
	v_exp_f32_e32 v33, v32
	v_sub_f32_e32 v32, v35, v37
	v_exp_f32_e32 v32, v32
	v_mov_b32_e32 v252, 0x1fcf
	v_add_f32_e32 v35, v33, v32
	v_div_scale_f32 v36, s[2:3], v35, v35, 1.0
	v_rcp_f32_e32 v38, v36
	v_div_scale_f32 v39, vcc, 1.0, v35, 1.0
	v_fma_f32 v40, -v36, v38, 1.0
	v_fmac_f32_e32 v38, v40, v38
	v_mul_f32_e32 v40, v39, v38
	v_fma_f32 v41, -v36, v40, v39
	v_fmac_f32_e32 v40, v41, v38
	v_fma_f32 v36, -v36, v40, v39
	v_log_f32_e32 v39, v35
	v_div_fmas_f32 v36, v36, v38, v40
	v_div_fixup_f32 v36, v36, v35, 1.0
	v_pk_mul_f32 v[32:33], v[32:33], v[36:37] op_sel_hi:[1,0]
	v_add_f32_e32 v35, v37, v39
	s_and_saveexec_b64 s[28:29], s[98:99]
	s_cbranch_execnz .LBB0_120
	s_branch .LBB0_121
